# dilated attention: K rows by LDS-DMA (global_load_lds) into two alternating unpadded XOR-swizzled K images; no K registers, no K ds_writes; static LDS 28688
# speedup vs baseline: 1.0062x; 1.0011x over previous
.LBB0_315:
	s_ashr_i32 s11, s10, 4
	s_mul_hi_i32 s14, s11, 0x55555556
	s_lshr_b32 s15, s14, 31
	s_add_i32 s14, s14, s15
	s_and_b32 s6, s10, 15
	s_mul_i32 s14, s14, 3
	s_mul_hi_i32 s10, s10, 0x2aaaaaab
	s_sub_i32 s18, s11, s14
	s_lshr_b32 s11, s10, 31
	s_ashr_i32 s10, s10, 3
	s_add_i32 s10, s10, s11
	s_and_b32 s16, s10, 7
	s_ashr_i32 s20, s10, 3
	s_lshl_b32 s10, s18, 1
	s_bfm_b32 s11, s10, 0
	s_lshr_b32 s15, s6, s10
	s_and_b32 s11, s11, s6
	s_ashr_i32 s21, s20, 31
	s_lshl_b32 s6, s15, 8
	s_load_dwordx2 s[12:13], s[58:59], 0x0
	s_lshl_b32 s14, 1, s10
	s_lshl_b64 s[20:21], s[20:21], 12
	s_lshl_b64 s[6:7], s[6:7], s10
	s_add_u32 s6, s6, s20
	s_addc_u32 s21, s7, s21
	s_or_b32 s20, s6, s11
	s_cmp_eq_u32 s15, 0
	v_cndmask_b32_e64 v2, 0, 1, s[8:9]
	s_cselect_b32 s17, 0x80, 0
	v_cmp_ne_u32_e64 s[6:7], 1, v2
	s_andn2_b64 vcc, exec, s[8:9]
	s_cbranch_vccnz .LBB0_329
	s_mov_b32 s15, 0
	s_lshl_b64 s[8:9], s[14:15], 7
	s_sub_u32 s11, s20, s8
	s_subb_u32 s19, s21, s9
	s_lshl_b64 s[8:9], 0xd00, s10
	s_mulk_i32 s19, 0xd00
	s_mul_hi_u32 s10, s11, 0xd00
	v_mov_b32_e32 v4, v0
	s_lshl_b32 s15, s16, 6
	s_add_i32 s19, s10, s19
	s_mulk_i32 s11, 0xd00
	s_add_u32 s10, s11, s15
	v_lshlrev_b32_e32 v2, 3, v4
	v_and_b32_e32 v2, 56, v2
	v_ashrrev_i32_e32 v5, 3, v4
	s_addc_u32 s11, s19, 0
	s_waitcnt vmcnt(0)
	s_waitcnt lgkmcnt(0)
	s_lshl_b64 s[66:67], s[10:11], 1
	s_add_u32 s66, s12, s66
	s_addc_u32 s67, s13, s67
	s_add_u32 s66, s66, 2560
	s_addc_u32 s67, s67, 0
	s_lshl_b32 s69, s8, 1
	v_bfe_u32 v232, v0, 4, 3
	v_and_b32_e32 v233, 7, v0
	v_xor_b32_e32 v233, v233, v232
	v_lshlrev_b32_e32 v233, 4, v233
	v_lshrrev_b32_e32 v232, 3, v0
	v_mad_u32_u24 v233, v232, s69, v233
	v_readfirstlane_b32 s68, v0
	s_lshr_b32 s68, s68, 6
	s_lshl_b32 s68, s68, 10
	s_add_u32 s68, s68, 0x1b010
	s_mov_b32 s71, 0x1b010
	s_lshl_b32 s60, s69, 6
	s_cmp_eq_u32 s17, 0
	s_cbranch_scc0 .Lkd_first0
	s_mov_b32 m0, s68
	s_nop 0
	global_load_lds_dwordx4 v233, s[66:67]
.Lkd_first0:
	s_add_u32 s66, s66, s60
	s_addc_u32 s67, s67, 0
	s_add_u32 s68, s68, 0x2000
	s_cmp_eq_u32 s17, 0
	s_cbranch_scc0 .Lkd_first1
	s_mov_b32 m0, s68
	s_nop 0
	global_load_lds_dwordx4 v233, s[66:67]
.Lkd_first1:
	s_add_u32 s66, s66, s60
	s_addc_u32 s67, s67, 0
	s_add_u32 s68, s68, 0x2000
	s_mov_b32 m0, s68
	s_nop 0
	global_load_lds_dwordx4 v233, s[66:67]
	s_add_u32 s66, s66, s60
	s_addc_u32 s67, s67, 0
	s_add_u32 s68, s68, 0x2000
	s_mov_b32 m0, s68
	s_nop 0
	global_load_lds_dwordx4 v233, s[66:67]
	s_add_u32 s66, s66, s60
	s_addc_u32 s67, s67, 0
	s_add_u32 s68, s68, 0x2000
	s_mov_b32 m0, s68
	s_nop 0
	global_load_lds_dwordx4 v233, s[66:67]
	s_add_u32 s66, s66, s60
	s_addc_u32 s67, s67, 0
	s_add_u32 s68, s68, 0x2000
	s_mov_b32 m0, s68
	s_nop 0
	global_load_lds_dwordx4 v233, s[66:67]
	s_add_u32 s66, s66, s60
	s_addc_u32 s67, s67, 0
	s_add_u32 s68, s68, 0x2000
	v_mov_b32_e32 v3, 0
	v_cmp_le_i32_e32 vcc, s17, v5
	v_lshlrev_b32_e32 v2, 1, v2
	s_and_saveexec_b64 s[22:23], vcc
	s_cbranch_execz .LBB0_318
	v_mad_u64_u32 v[6:7], s[24:25], s8, v5, 0
	v_mov_b32_e32 v8, v7
	v_mad_u64_u32 v[8:9], s[24:25], s9, v5, v[8:9]
	s_lshl_b64 s[24:25], s[10:11], 1
	s_waitcnt lgkmcnt(0)
	s_add_u32 s24, s12, s24
	v_mov_b32_e32 v7, v8
	s_addc_u32 s25, s13, s25
	v_lshl_add_u64 v[6:7], v[6:7], 1, s[24:25]
	v_lshl_add_u64 v[6:7], v[6:7], 0, v[2:3]
	global_load_dwordx4 v[18:21], v[6:7], off offset:3584
.LBB0_318:
	s_or_b64 exec, exec, s[22:23]
	v_add_u32_e32 v3, 0x200, v4
	v_ashrrev_i32_e32 v3, 3, v3
	v_cmp_le_i32_e32 vcc, s17, v3
	s_and_saveexec_b64 s[22:23], vcc
	s_cbranch_execz .LBB0_320
	v_mad_u64_u32 v[6:7], s[24:25], s8, v3, 0
	v_mov_b32_e32 v8, v7
	v_mad_u64_u32 v[8:9], s[24:25], s9, v3, v[8:9]
	s_lshl_b64 s[24:25], s[10:11], 1
	s_waitcnt lgkmcnt(0)
	s_add_u32 s24, s12, s24
	v_mov_b32_e32 v7, v8
	s_addc_u32 s25, s13, s25
	v_lshl_add_u64 v[6:7], v[6:7], 1, s[24:25]
	v_mov_b32_e32 v3, 0
	v_lshl_add_u64 v[6:7], v[6:7], 0, v[2:3]
	global_load_dwordx4 v[26:29], v[6:7], off offset:3584
.LBB0_320:
	s_or_b64 exec, exec, s[22:23]
	v_add_u32_e32 v3, 0x400, v4
	v_ashrrev_i32_e32 v3, 3, v3
	v_cmp_le_i32_e32 vcc, s17, v3
	s_and_saveexec_b64 s[22:23], vcc
	s_cbranch_execz .LBB0_322
	v_mad_u64_u32 v[6:7], s[24:25], s8, v3, 0
	v_mov_b32_e32 v8, v7
	v_mad_u64_u32 v[8:9], s[24:25], s9, v3, v[8:9]
	s_lshl_b64 s[24:25], s[10:11], 1
	s_waitcnt lgkmcnt(0)
	s_add_u32 s24, s12, s24
	v_mov_b32_e32 v7, v8
	s_addc_u32 s25, s13, s25
	v_lshl_add_u64 v[6:7], v[6:7], 1, s[24:25]
	v_mov_b32_e32 v3, 0
	v_lshl_add_u64 v[6:7], v[6:7], 0, v[2:3]
	global_load_dwordx4 v[34:37], v[6:7], off offset:3584
.LBB0_322:
	s_or_b64 exec, exec, s[22:23]
	v_add_u32_e32 v3, 0x600, v4
	v_ashrrev_i32_e32 v3, 3, v3
	v_cmp_le_i32_e32 vcc, s17, v3
	s_and_saveexec_b64 s[22:23], vcc
	s_cbranch_execz .LBB0_324
	v_mad_u64_u32 v[6:7], s[24:25], s8, v3, 0
	v_mov_b32_e32 v8, v7
	v_mad_u64_u32 v[8:9], s[24:25], s9, v3, v[8:9]
	s_lshl_b64 s[24:25], s[10:11], 1
	s_waitcnt lgkmcnt(0)
	s_add_u32 s24, s12, s24
	v_mov_b32_e32 v7, v8
	s_addc_u32 s25, s13, s25
	v_lshl_add_u64 v[6:7], v[6:7], 1, s[24:25]
	v_mov_b32_e32 v3, 0
	v_lshl_add_u64 v[6:7], v[6:7], 0, v[2:3]
	global_load_dwordx4 v[42:45], v[6:7], off offset:3584
.LBB0_324:
	s_or_b64 exec, exec, s[22:23]
	v_add_u32_e32 v3, 0x800, v4
	v_ashrrev_i32_e32 v3, 3, v3
	v_cmp_le_i32_e32 vcc, s17, v3
	s_and_saveexec_b64 s[22:23], vcc
	s_cbranch_execz .LBB0_326
	v_mad_u64_u32 v[6:7], s[24:25], s8, v3, 0
	v_mov_b32_e32 v8, v7
	v_mad_u64_u32 v[8:9], s[24:25], s9, v3, v[8:9]
	s_lshl_b64 s[24:25], s[10:11], 1
	s_waitcnt lgkmcnt(0)
	s_add_u32 s24, s12, s24
	v_mov_b32_e32 v7, v8
	s_addc_u32 s25, s13, s25
	v_lshl_add_u64 v[6:7], v[6:7], 1, s[24:25]
	v_mov_b32_e32 v3, 0
	v_lshl_add_u64 v[6:7], v[6:7], 0, v[2:3]
	global_load_dwordx4 v[50:53], v[6:7], off offset:3584
.LBB0_326:
	s_or_b64 exec, exec, s[22:23]
	v_add_u32_e32 v3, 0xa00, v4
	v_ashrrev_i32_e32 v3, 3, v3
	v_cmp_le_i32_e32 vcc, s17, v3
	s_and_saveexec_b64 s[22:23], vcc
	s_cbranch_execz .LBB0_328
	v_mad_u64_u32 v[6:7], s[24:25], s8, v3, 0
	v_mov_b32_e32 v8, v7
	s_lshl_b64 s[10:11], s[10:11], 1
	v_mad_u64_u32 v[8:9], s[24:25], s9, v3, v[8:9]
	s_waitcnt lgkmcnt(0)
	s_add_u32 s10, s12, s10
	v_mov_b32_e32 v7, v8
	s_addc_u32 s11, s13, s11
	v_lshl_add_u64 v[6:7], v[6:7], 1, s[10:11]
	v_mov_b32_e32 v3, 0
	v_lshl_add_u64 v[2:3], v[6:7], 0, v[2:3]
	global_load_dwordx4 v[58:61], v[2:3], off offset:3584

.LBB0_331:
	s_waitcnt vmcnt(6)
	v_mov_b64_e32 v[78:79], v[98:99]
	v_mov_b64_e32 v[82:83], v[94:95]
	v_mov_b64_e32 v[70:71], v[90:91]
	v_mov_b64_e32 v[74:75], v[86:87]
	s_andn2_b64 vcc, exec, s[26:27]
	v_mov_b64_e32 v[80:81], v[100:101]
	v_mov_b64_e32 v[84:85], v[96:97]
	v_mov_b64_e32 v[72:73], v[92:93]
	v_mov_b64_e32 v[76:77], v[88:89]
	s_mov_b32 s16, s49
	s_mov_b32 s17, s29
	s_mov_b32 s18, s48
	s_mov_b64 s[20:21], s[30:31]
	s_mov_b32 s14, s28
	s_sub_u32 s71, 0x1b020, s71
	s_cbranch_vccz .Lgq_entry
	s_barrier
.LBB0_332:
	v_mov_b32_e32 v1, v0
	s_nop 0
	v_lshlrev_b32_e32 v2, 4, v1
	v_and_b32_e32 v2, 0x70, v2
	v_ashrrev_i32_e32 v3, 3, v1
	v_add_u32_e32 v2, 16, v2
	v_cmp_le_i32_e32 vcc, s17, v3
	s_and_saveexec_b64 s[6:7], vcc
	s_cbranch_execz .LBB0_334
	v_mad_u64_u32 v[4:5], s[10:11], v3, s41, v[2:3]
	ds_write_b128 v4, v[18:21] offset:55296
.LBB0_334:
	s_or_b64 exec, exec, s[6:7]
	v_add_u32_e32 v3, 0x200, v1
	v_ashrrev_i32_e32 v3, 3, v3
	v_cmp_le_i32_e32 vcc, s17, v3
	s_and_saveexec_b64 s[6:7], vcc
	s_cbranch_execz .LBB0_336
	v_mad_u64_u32 v[4:5], s[10:11], v3, s41, v[2:3]
	ds_write_b128 v4, v[26:29] offset:55296
.LBB0_336:
	s_or_b64 exec, exec, s[6:7]
	v_add_u32_e32 v3, 0x400, v1
	v_ashrrev_i32_e32 v3, 3, v3
	v_cmp_le_i32_e32 vcc, s17, v3
	s_and_saveexec_b64 s[6:7], vcc
	s_cbranch_execz .LBB0_338
	v_mad_u64_u32 v[4:5], s[10:11], v3, s41, v[2:3]
	ds_write_b128 v4, v[34:37] offset:55296
.LBB0_338:
	s_or_b64 exec, exec, s[6:7]
	v_add_u32_e32 v3, 0x600, v1
	v_ashrrev_i32_e32 v3, 3, v3
	v_cmp_le_i32_e32 vcc, s17, v3
	s_and_saveexec_b64 s[6:7], vcc
	s_cbranch_execz .LBB0_340
	v_mad_u64_u32 v[4:5], s[10:11], v3, s41, v[2:3]
	ds_write_b128 v4, v[42:45] offset:55296
.LBB0_340:
	s_or_b64 exec, exec, s[6:7]
	v_add_u32_e32 v3, 0x800, v1
	v_ashrrev_i32_e32 v3, 3, v3
	v_cmp_le_i32_e32 vcc, s17, v3
	s_and_saveexec_b64 s[6:7], vcc
	s_cbranch_execz .LBB0_342
	v_mad_u64_u32 v[4:5], s[10:11], v3, s41, v[2:3]
	ds_write_b128 v4, v[50:53] offset:55296
.LBB0_342:
	s_or_b64 exec, exec, s[6:7]
	v_add_u32_e32 v1, 0xa00, v1
	v_ashrrev_i32_e32 v1, 3, v1
	v_cmp_le_i32_e32 vcc, s17, v1
	s_and_saveexec_b64 s[6:7], vcc
	s_cbranch_execz .LBB0_344
	v_mad_u64_u32 v[2:3], s[10:11], v1, s41, v[2:3]
	ds_write_b128 v2, v[58:61] offset:55296

.LBB0_361:
	v_lshrrev_b32_e32 v15, 6, v0
	v_and_b32_e32 v16, 15, v0
	v_bfe_u32 v148, v0, 4, 2
	v_readfirstlane_b32 s92, v15
	v_lshl_or_b32 v17, v15, 5, v16
	v_lshlrev_b32_e32 v146, 2, v148
	v_sub_u32_e32 v14, v16, v146
	v_mov_b32_e32 v15, 0x90
	v_bfe_u32 v232, v0, 1, 3
	v_xor_b32_e32 v232, v148, v232
	v_lshlrev_b32_e32 v232, 4, v232
	v_lshl_add_u32 v194, v17, 7, v232
	v_xor_b32_e32 v232, 64, v232
	v_lshl_add_u32 v232, v17, 7, v232
	v_add_u32_e32 v194, s71, v194
	v_add_u32_e32 v232, s71, v232
	v_lshrrev_b32_e32 v195, 2, v16
	v_add_u32_e32 v195, v195, v146
	v_lshl_add_u32 v195, s92, 5, v195
	v_mul_u32_u24_e32 v195, v195, v15
	v_and_b32_e32 v16, 3, v0
	v_lshl_add_u32 v195, v16, 3, v195
	v_add_u32_e32 v195, 0xd810, v195
	ds_read_b128 v[178:181], v194 offset:0
	ds_read_b128 v[182:185], v232 offset:0
	ds_read_b128 v[186:189], v194 offset:2048
	ds_read_b128 v[190:193], v232 offset:2048
	ds_read_b64_tr_b16 v[200:201], v195 offset:0
	ds_read_b64_tr_b16 v[202:203], v195 offset:2304
	ds_read_b64_tr_b16 v[204:205], v195 offset:32
	ds_read_b64_tr_b16 v[206:207], v195 offset:2336
	ds_read_b64_tr_b16 v[208:209], v195 offset:64
	ds_read_b64_tr_b16 v[210:211], v195 offset:2368
	ds_read_b64_tr_b16 v[212:213], v195 offset:96
	ds_read_b64_tr_b16 v[214:215], v195 offset:2400
	v_lshrrev_b32_e32 v15, 3, v0
	v_and_b32_e32 v16, 7, v0
	v_lshlrev_b32_e32 v16, 4, v16
	v_mad_u32_u24 v196, v15, s95, v16
	v_and_b32_e32 v16, 48, v0
	v_mad_u32_u24 v198, v17, s95, v16
	v_bfe_u32 v233, v0, 4, 3
	v_and_b32_e32 v16, 7, v0
	v_xor_b32_e32 v16, v16, v233
	v_lshlrev_b32_e32 v16, 4, v16
	v_mad_u32_u24 v233, v15, s95, v16
	s_sub_u32 s68, 0x1b020, s71
	s_lshl_b32 s69, s92, 10
	s_add_u32 s68, s68, s69
	s_add_u32 s66, s96, 2560
	s_addc_u32 s67, s97, 0
	s_lshl_b32 s60, s95, 6
	s_lshl_b32 s61, s95, 4
	s_sub_i32 s93, 4, s92
	s_max_i32 s93, s93, 0
	s_cmp_eq_u32 s17, 0
	s_cselect_b32 s93, 0, s93
	v_cmp_le_i32_e64 s[76:77], v14, 0
	v_cmp_le_i32_e64 s[78:79], v14, 1
	v_cmp_le_i32_e64 s[80:81], v14, 2
	v_cmp_le_i32_e64 s[82:83], v14, 3
	v_cmp_ge_i32_e64 s[84:85], v14, 0
	v_cmp_ge_i32_e64 s[86:87], v14, 1
	v_cmp_ge_i32_e64 s[88:89], v14, 2
	v_cmp_ge_i32_e64 s[90:91], v14, 3
	v_mov_b32_e32 v10, 0x3f803f80
	v_mov_b32_e32 v11, v10
	v_mov_b32_e32 v12, v10
	v_mov_b32_e32 v13, v10
	v_mov_b32_e32 v138, 0
	v_mov_b32_e32 v139, 0
	v_mov_b32_e32 v140, 0
	v_mov_b32_e32 v141, 0
	v_mov_b32_e32 v118, 0
	v_mov_b32_e32 v119, 0
	v_mov_b32_e32 v120, 0
	v_mov_b32_e32 v121, 0
	v_mov_b32_e32 v134, 0
	v_mov_b32_e32 v135, 0
	v_mov_b32_e32 v136, 0
	v_mov_b32_e32 v137, 0
	v_mov_b32_e32 v130, 0
	v_mov_b32_e32 v131, 0
	v_mov_b32_e32 v132, 0
	v_mov_b32_e32 v133, 0
	v_mov_b32_e32 v126, 0
	v_mov_b32_e32 v127, 0
	v_mov_b32_e32 v128, 0
	v_mov_b32_e32 v129, 0
	v_mov_b32_e32 v122, 0
	v_mov_b32_e32 v123, 0
	v_mov_b32_e32 v124, 0
	v_mov_b32_e32 v125, 0
	v_mov_b32_e32 v114, 0
	v_mov_b32_e32 v115, 0
	v_mov_b32_e32 v116, 0
	v_mov_b32_e32 v117, 0
	v_mov_b32_e32 v106, 0
	v_mov_b32_e32 v107, 0
	v_mov_b32_e32 v108, 0
	v_mov_b32_e32 v109, 0
	v_mov_b32_e32 v110, 0
	v_mov_b32_e32 v111, 0
	v_mov_b32_e32 v112, 0
	v_mov_b32_e32 v113, 0
	v_mov_b32_e32 v102, 0
	v_mov_b32_e32 v103, 0
	v_mov_b32_e32 v104, 0
	v_mov_b32_e32 v105, 0
	s_waitcnt lgkmcnt(8)
	v_mfma_f32_16x16x32_bf16 v[150:153], v[178:181], v[74:77], v[66:69]
	v_mfma_f32_16x16x32_bf16 v[154:157], v[186:189], v[74:77], v[66:69]
	v_mfma_f32_16x16x32_bf16 v[162:165], v[186:189], v[82:85], v[66:69]
	v_mfma_f32_16x16x32_bf16 v[150:153], v[182:185], v[70:73], v[150:153]
	v_mfma_f32_16x16x32_bf16 v[154:157], v[190:193], v[70:73], v[154:157]
	v_mfma_f32_16x16x32_bf16 v[162:165], v[190:193], v[78:81], v[162:165]
	s_waitcnt lgkmcnt(0)
	ds_read_b128 v[178:181], v194 offset:4096
	ds_read_b128 v[182:185], v232 offset:4096
	ds_read_b128 v[186:189], v194 offset:6144
	ds_read_b128 v[190:193], v232 offset:6144
	ds_read_b64_tr_b16 v[216:217], v195 offset:4608
	ds_read_b64_tr_b16 v[218:219], v195 offset:6912
	ds_read_b64_tr_b16 v[220:221], v195 offset:4640
	ds_read_b64_tr_b16 v[222:223], v195 offset:6944
	ds_read_b64_tr_b16 v[224:225], v195 offset:4672
	ds_read_b64_tr_b16 v[226:227], v195 offset:6976
	ds_read_b64_tr_b16 v[228:229], v195 offset:4704
	ds_read_b64_tr_b16 v[230:231], v195 offset:7008
.Lattn_blk0:
	s_cmp_eq_u32 s94, 0
	s_cbranch_scc1 .Lattn_ldskip0lo
	s_cmp_lt_u32 s92, 4
	s_cbranch_scc0 .Lattn_ldskip0lo
	s_cmp_eq_u32 s29, 0
	s_cbranch_scc0 .Lattn_ldadv0lo_0
	s_mov_b32 m0, s68
	s_nop 0
	global_load_lds_dwordx4 v233, s[66:67]
	global_load_dwordx4 v[18:21], v196, s[96:97] offset:3584
.Lattn_ldadv0lo_0:
	s_add_u32 s96, s96, s60
	s_addc_u32 s97, s97, 0
	s_add_u32 s66, s66, s60
	s_addc_u32 s67, s67, 0
	s_add_u32 s68, s68, 0x2000
	s_cmp_eq_u32 s29, 0
	s_cbranch_scc0 .Lattn_ldadv0lo_1
	s_mov_b32 m0, s68
	s_nop 0
	global_load_lds_dwordx4 v233, s[66:67]
	global_load_dwordx4 v[26:29], v196, s[96:97] offset:3584
.Lattn_ldadv0lo_1:
	s_add_u32 s96, s96, s60
	s_addc_u32 s97, s97, 0
	s_add_u32 s66, s66, s60
	s_addc_u32 s67, s67, 0
	s_add_u32 s68, s68, 0x2000
	s_mov_b32 m0, s68
	s_nop 0
	global_load_lds_dwordx4 v233, s[66:67]
	global_load_dwordx4 v[34:37], v196, s[96:97] offset:3584
	s_add_u32 s96, s96, s60
	s_addc_u32 s97, s97, 0
	s_add_u32 s66, s66, s60
	s_addc_u32 s67, s67, 0
	s_add_u32 s68, s68, 0x2000
.Lattn_ldskip0lo:
	s_cmp_eq_u32 s94, 0
	s_cbranch_scc1 .Lattn_ldskip0hi
	s_cmp_lt_u32 s92, 4
	s_cbranch_scc1 .Lattn_ldskip0hi
	s_cmp_eq_u32 s29, 0
	s_cbranch_scc0 .Lattn_ldadv0hi_0
	s_mov_b32 m0, s68
	s_nop 0
	global_load_lds_dwordx4 v233, s[66:67]
	global_load_dwordx4 v[18:21], v196, s[96:97] offset:3584

.Lattn_ldskip0hi:
	s_cmp_le_u32 s93, 0
	s_cbranch_scc0 .Lattn_min0
	s_waitcnt lgkmcnt(8)
	v_mfma_f32_16x16x32_bf16 v[166:169], v[178:181], v[74:77], v[66:69]
	v_exp_f32_e32 v150, v150
	v_mfma_f32_16x16x32_bf16 v[244:247], v[178:181], v[82:85], v[66:69]
	v_exp_f32_e32 v151, v151
	v_mfma_f32_16x16x32_bf16 v[170:173], v[186:189], v[74:77], v[66:69]
	v_exp_f32_e32 v152, v152
	v_mfma_f32_16x16x32_bf16 v[248:251], v[186:189], v[82:85], v[66:69]
	v_exp_f32_e32 v153, v153
	v_mfma_f32_16x16x32_bf16 v[166:169], v[182:185], v[70:73], v[166:169]
	v_exp_f32_e32 v154, v154
	v_mfma_f32_16x16x32_bf16 v[244:247], v[182:185], v[78:81], v[244:247]
	v_exp_f32_e32 v155, v155
	v_mfma_f32_16x16x32_bf16 v[170:173], v[190:193], v[70:73], v[170:173]
	v_exp_f32_e32 v156, v156
	v_mfma_f32_16x16x32_bf16 v[248:251], v[190:193], v[78:81], v[248:251]
	v_exp_f32_e32 v157, v157
	s_nop 0
	v_cndmask_b32_e64 v150, 0, v150, s[76:77]
	v_cndmask_b32_e64 v151, 0, v151, s[78:79]
	v_cndmask_b32_e64 v152, 0, v152, s[80:81]
	v_cndmask_b32_e64 v153, 0, v153, s[82:83]
	v_cvt_pk_bf16_f32 v2, v150, v151
	v_cvt_pk_bf16_f32 v3, v152, v153
	v_cvt_pk_bf16_f32 v4, v154, v155
	v_cvt_pk_bf16_f32 v5, v156, v157
	v_exp_f32_e32 v162, v162
	v_exp_f32_e32 v163, v163
	v_mfma_f32_16x16x32_bf16 v[138:141], v[10:13], v[2:5], v[138:141]
	v_exp_f32_e32 v164, v164
	v_exp_f32_e32 v165, v165
	v_mfma_f32_16x16x32_bf16 v[134:137], v[200:203], v[2:5], v[134:137]
	v_mfma_f32_16x16x32_bf16 v[130:133], v[204:207], v[2:5], v[130:133]
	v_mfma_f32_16x16x32_bf16 v[126:129], v[208:211], v[2:5], v[126:129]
	v_mfma_f32_16x16x32_bf16 v[122:125], v[212:215], v[2:5], v[122:125]
	s_nop 0
	v_mov_b32_e32 v6, 0
	v_mov_b32_e32 v7, 0
	v_cndmask_b32_e64 v162, 0, v162, s[76:77]
	v_cndmask_b32_e64 v163, 0, v163, s[78:79]
	v_cndmask_b32_e64 v164, 0, v164, s[80:81]
	v_cndmask_b32_e64 v165, 0, v165, s[82:83]
	v_cvt_pk_bf16_f32 v8, v162, v163
	v_cvt_pk_bf16_f32 v9, v164, v165
	s_waitcnt lgkmcnt(0)
	s_nop 1
	v_mfma_f32_16x16x32_bf16 v[118:121], v[10:13], v[6:9], v[118:121]
	ds_read_b128 v[178:181], v194 offset:8192
	v_mfma_f32_16x16x32_bf16 v[114:117], v[200:203], v[6:9], v[114:117]
	ds_read_b128 v[182:185], v232 offset:8192
	v_mfma_f32_16x16x32_bf16 v[106:109], v[204:207], v[6:9], v[106:109]
	ds_read_b128 v[186:189], v194 offset:10240
	v_mfma_f32_16x16x32_bf16 v[110:113], v[208:211], v[6:9], v[110:113]
	ds_read_b128 v[190:193], v232 offset:10240
	v_mfma_f32_16x16x32_bf16 v[102:105], v[212:215], v[6:9], v[102:105]
	ds_read_b64_tr_b16 v[200:201], v195 offset:9216
	ds_read_b64_tr_b16 v[202:203], v195 offset:11520
	ds_read_b64_tr_b16 v[204:205], v195 offset:9248
	ds_read_b64_tr_b16 v[206:207], v195 offset:11552
	ds_read_b64_tr_b16 v[208:209], v195 offset:9280
	ds_read_b64_tr_b16 v[210:211], v195 offset:11584
	ds_read_b64_tr_b16 v[212:213], v195 offset:9312
	ds_read_b64_tr_b16 v[214:215], v195 offset:11616
	s_branch .Lattn_end0
.Lattn_min0:
	s_waitcnt lgkmcnt(8)
	v_mfma_f32_16x16x32_bf16 v[166:169], v[178:181], v[74:77], v[66:69]
	v_mfma_f32_16x16x32_bf16 v[244:247], v[178:181], v[82:85], v[66:69]
	v_mfma_f32_16x16x32_bf16 v[170:173], v[186:189], v[74:77], v[66:69]
	v_mfma_f32_16x16x32_bf16 v[248:251], v[186:189], v[82:85], v[66:69]
	v_mfma_f32_16x16x32_bf16 v[166:169], v[182:185], v[70:73], v[166:169]
	v_mfma_f32_16x16x32_bf16 v[244:247], v[182:185], v[78:81], v[244:247]
	v_mfma_f32_16x16x32_bf16 v[170:173], v[190:193], v[70:73], v[170:173]
	v_mfma_f32_16x16x32_bf16 v[248:251], v[190:193], v[78:81], v[248:251]
	s_waitcnt lgkmcnt(0)
	ds_read_b128 v[178:181], v194 offset:8192
	ds_read_b128 v[182:185], v232 offset:8192
	ds_read_b128 v[186:189], v194 offset:10240
	ds_read_b128 v[190:193], v232 offset:10240
	ds_read_b64_tr_b16 v[200:201], v195 offset:9216
	ds_read_b64_tr_b16 v[202:203], v195 offset:11520
	ds_read_b64_tr_b16 v[204:205], v195 offset:9248
	ds_read_b64_tr_b16 v[206:207], v195 offset:11552
	ds_read_b64_tr_b16 v[208:209], v195 offset:9280
	ds_read_b64_tr_b16 v[210:211], v195 offset:11584
	ds_read_b64_tr_b16 v[212:213], v195 offset:9312
	ds_read_b64_tr_b16 v[214:215], v195 offset:11616
.Lattn_end0:
.Lattn_blk1:
	s_cmp_eq_u32 s94, 0
	s_cbranch_scc1 .Lattn_ldskip1lo
	s_cmp_lt_u32 s92, 4
	s_cbranch_scc0 .Lattn_ldskip1lo
	s_mov_b32 m0, s68
	s_nop 0
	global_load_lds_dwordx4 v233, s[66:67]
	global_load_dwordx4 v[42:45], v196, s[96:97] offset:3584
	s_add_u32 s96, s96, s60
	s_addc_u32 s97, s97, 0
	s_add_u32 s66, s66, s60
	s_addc_u32 s67, s67, 0
	s_add_u32 s68, s68, 0x2000
	s_mov_b32 m0, s68
	s_nop 0
	global_load_lds_dwordx4 v233, s[66:67]
	global_load_dwordx4 v[50:53], v196, s[96:97] offset:3584
	s_add_u32 s96, s96, s60
	s_addc_u32 s97, s97, 0
	s_add_u32 s66, s66, s60
	s_addc_u32 s67, s67, 0
	s_add_u32 s68, s68, 0x2000
	s_mov_b32 m0, s68
	s_nop 0
	global_load_lds_dwordx4 v233, s[66:67]
	global_load_dwordx4 v[58:61], v196, s[96:97] offset:3584
	s_add_u32 s96, s96, s60
	s_addc_u32 s97, s97, 0
	s_add_u32 s66, s66, s60
	s_addc_u32 s67, s67, 0
	s_add_u32 s68, s68, 0x2000
	global_load_dwordx4 v[86:89], v198, s[98:99] offset:1536
	global_load_dwordx4 v[90:93], v198, s[98:99] offset:1600
	s_add_u32 s98, s98, s61
	s_addc_u32 s99, s99, 0
	global_load_dwordx4 v[94:97], v198, s[98:99] offset:1536
	global_load_dwordx4 v[98:101], v198, s[98:99] offset:1600
.Lattn_ldskip1lo:
	s_cmp_eq_u32 s94, 0
	s_cbranch_scc1 .Lattn_ldskip1hi
	s_cmp_lt_u32 s92, 4
	s_cbranch_scc1 .Lattn_ldskip1hi
	s_mov_b32 m0, s68
	s_nop 0
	global_load_lds_dwordx4 v233, s[66:67]
	global_load_dwordx4 v[42:45], v196, s[96:97] offset:3584
	s_add_u32 s96, s96, s60
	s_addc_u32 s97, s97, 0
	s_add_u32 s66, s66, s60
	s_addc_u32 s67, s67, 0
	s_add_u32 s68, s68, 0x2000
	s_mov_b32 m0, s68
	s_nop 0
	global_load_lds_dwordx4 v233, s[66:67]
	global_load_dwordx4 v[50:53], v196, s[96:97] offset:3584
	s_add_u32 s96, s96, s60
	s_addc_u32 s97, s97, 0
	s_add_u32 s66, s66, s60
	s_addc_u32 s67, s67, 0
	s_add_u32 s68, s68, 0x2000
	s_mov_b32 m0, s68
	s_nop 0
	global_load_lds_dwordx4 v233, s[66:67]
	global_load_dwordx4 v[58:61], v196, s[96:97] offset:3584
	s_add_u32 s96, s96, s60
	s_addc_u32 s97, s97, 0
	s_add_u32 s66, s66, s60
	s_addc_u32 s67, s67, 0
	s_add_u32 s68, s68, 0x2000
	global_load_dwordx4 v[86:89], v198, s[98:99] offset:1536
	global_load_dwordx4 v[90:93], v198, s[98:99] offset:1600
	s_add_u32 s98, s98, s61
	s_addc_u32 s99, s99, 0
	global_load_dwordx4 v[94:97], v198, s[98:99] offset:1536
	global_load_dwordx4 v[98:101], v198, s[98:99] offset:1600
.Lattn_ldskip1hi:
	s_cmp_le_u32 s93, 1
	s_cbranch_scc0 .Lattn_min1
	s_waitcnt lgkmcnt(8)
	v_mfma_f32_16x16x32_bf16 v[150:153], v[178:181], v[74:77], v[66:69]
	v_exp_f32_e32 v166, v166
	v_mfma_f32_16x16x32_bf16 v[158:161], v[178:181], v[82:85], v[66:69]
	v_exp_f32_e32 v167, v167
	v_mfma_f32_16x16x32_bf16 v[154:157], v[186:189], v[74:77], v[66:69]
	v_exp_f32_e32 v168, v168
	v_mfma_f32_16x16x32_bf16 v[162:165], v[186:189], v[82:85], v[66:69]
	v_exp_f32_e32 v169, v169
	v_mfma_f32_16x16x32_bf16 v[150:153], v[182:185], v[70:73], v[150:153]
	v_exp_f32_e32 v170, v170
	v_mfma_f32_16x16x32_bf16 v[158:161], v[182:185], v[78:81], v[158:161]
	v_exp_f32_e32 v171, v171
	v_mfma_f32_16x16x32_bf16 v[154:157], v[190:193], v[70:73], v[154:157]
	v_exp_f32_e32 v172, v172
	v_mfma_f32_16x16x32_bf16 v[162:165], v[190:193], v[78:81], v[162:165]
	v_exp_f32_e32 v173, v173
	s_nop 0
	v_cvt_pk_bf16_f32 v2, v166, v167
	v_cvt_pk_bf16_f32 v3, v168, v169
	v_cvt_pk_bf16_f32 v4, v170, v171
	v_cvt_pk_bf16_f32 v5, v172, v173
	v_exp_f32_e32 v244, v244
	v_exp_f32_e32 v245, v245
	v_mfma_f32_16x16x32_bf16 v[138:141], v[10:13], v[2:5], v[138:141]
	v_exp_f32_e32 v246, v246
	v_exp_f32_e32 v247, v247
	v_mfma_f32_16x16x32_bf16 v[134:137], v[216:219], v[2:5], v[134:137]
	v_exp_f32_e32 v248, v248
	v_exp_f32_e32 v249, v249
	v_mfma_f32_16x16x32_bf16 v[130:133], v[220:223], v[2:5], v[130:133]
	v_exp_f32_e32 v250, v250
	v_exp_f32_e32 v251, v251
	v_mfma_f32_16x16x32_bf16 v[126:129], v[224:227], v[2:5], v[126:129]
	v_mfma_f32_16x16x32_bf16 v[122:125], v[228:231], v[2:5], v[122:125]
	s_nop 0
	v_cvt_pk_bf16_f32 v6, v244, v245
	v_cvt_pk_bf16_f32 v7, v246, v247
	v_cvt_pk_bf16_f32 v8, v248, v249
	v_cvt_pk_bf16_f32 v9, v250, v251
	s_waitcnt lgkmcnt(0)
	s_nop 1
	v_mfma_f32_16x16x32_bf16 v[118:121], v[10:13], v[6:9], v[118:121]
	ds_read_b128 v[178:181], v194 offset:12288
	v_mfma_f32_16x16x32_bf16 v[114:117], v[216:219], v[6:9], v[114:117]
	ds_read_b128 v[182:185], v232 offset:12288
	v_mfma_f32_16x16x32_bf16 v[106:109], v[220:223], v[6:9], v[106:109]
	ds_read_b128 v[186:189], v194 offset:14336
	v_mfma_f32_16x16x32_bf16 v[110:113], v[224:227], v[6:9], v[110:113]
	ds_read_b128 v[190:193], v232 offset:14336
	v_mfma_f32_16x16x32_bf16 v[102:105], v[228:231], v[6:9], v[102:105]
	ds_read_b64_tr_b16 v[216:217], v195 offset:13824
	ds_read_b64_tr_b16 v[218:219], v195 offset:16128
	ds_read_b64_tr_b16 v[220:221], v195 offset:13856
	ds_read_b64_tr_b16 v[222:223], v195 offset:16160
	ds_read_b64_tr_b16 v[224:225], v195 offset:13888
	ds_read_b64_tr_b16 v[226:227], v195 offset:16192
	ds_read_b64_tr_b16 v[228:229], v195 offset:13920
	ds_read_b64_tr_b16 v[230:231], v195 offset:16224
	s_branch .Lattn_end1
.Lattn_min1:
	s_waitcnt lgkmcnt(8)
	v_mfma_f32_16x16x32_bf16 v[150:153], v[178:181], v[74:77], v[66:69]
	v_mfma_f32_16x16x32_bf16 v[158:161], v[178:181], v[82:85], v[66:69]
	v_mfma_f32_16x16x32_bf16 v[154:157], v[186:189], v[74:77], v[66:69]
	v_mfma_f32_16x16x32_bf16 v[162:165], v[186:189], v[82:85], v[66:69]
	v_mfma_f32_16x16x32_bf16 v[150:153], v[182:185], v[70:73], v[150:153]
	v_mfma_f32_16x16x32_bf16 v[158:161], v[182:185], v[78:81], v[158:161]
	v_mfma_f32_16x16x32_bf16 v[154:157], v[190:193], v[70:73], v[154:157]
	v_mfma_f32_16x16x32_bf16 v[162:165], v[190:193], v[78:81], v[162:165]
	s_waitcnt lgkmcnt(0)
	ds_read_b128 v[178:181], v194 offset:12288
	ds_read_b128 v[182:185], v232 offset:12288
	ds_read_b128 v[186:189], v194 offset:14336
	ds_read_b128 v[190:193], v232 offset:14336
	ds_read_b64_tr_b16 v[216:217], v195 offset:13824
	ds_read_b64_tr_b16 v[218:219], v195 offset:16128
	ds_read_b64_tr_b16 v[220:221], v195 offset:13856
	ds_read_b64_tr_b16 v[222:223], v195 offset:16160
	ds_read_b64_tr_b16 v[224:225], v195 offset:13888
	ds_read_b64_tr_b16 v[226:227], v195 offset:16192
	ds_read_b64_tr_b16 v[228:229], v195 offset:13920
	ds_read_b64_tr_b16 v[230:231], v195 offset:16224
.Lattn_end1:
.Lattn_blk2:
	s_cmp_le_u32 s93, 2
	s_cbranch_scc0 .Lattn_min2
	s_waitcnt lgkmcnt(8)
	v_mfma_f32_16x16x32_bf16 v[166:169], v[178:181], v[74:77], v[66:69]
	v_exp_f32_e32 v150, v150
	v_mfma_f32_16x16x32_bf16 v[244:247], v[178:181], v[82:85], v[66:69]
	v_exp_f32_e32 v151, v151
	v_mfma_f32_16x16x32_bf16 v[170:173], v[186:189], v[74:77], v[66:69]
	v_exp_f32_e32 v152, v152
	v_mfma_f32_16x16x32_bf16 v[248:251], v[186:189], v[82:85], v[66:69]
	v_exp_f32_e32 v153, v153
	v_mfma_f32_16x16x32_bf16 v[166:169], v[182:185], v[70:73], v[166:169]
	v_exp_f32_e32 v154, v154
	v_mfma_f32_16x16x32_bf16 v[244:247], v[182:185], v[78:81], v[244:247]
	v_exp_f32_e32 v155, v155
	v_mfma_f32_16x16x32_bf16 v[170:173], v[190:193], v[70:73], v[170:173]
	v_exp_f32_e32 v156, v156
	v_mfma_f32_16x16x32_bf16 v[248:251], v[190:193], v[78:81], v[248:251]
	v_exp_f32_e32 v157, v157
	s_nop 0
	v_cvt_pk_bf16_f32 v2, v150, v151
	v_cvt_pk_bf16_f32 v3, v152, v153
	v_cvt_pk_bf16_f32 v4, v154, v155
	v_cvt_pk_bf16_f32 v5, v156, v157
	v_exp_f32_e32 v158, v158
	v_exp_f32_e32 v159, v159
	v_mfma_f32_16x16x32_bf16 v[138:141], v[10:13], v[2:5], v[138:141]
	v_exp_f32_e32 v160, v160
	v_exp_f32_e32 v161, v161
	v_mfma_f32_16x16x32_bf16 v[134:137], v[200:203], v[2:5], v[134:137]
	v_exp_f32_e32 v162, v162
	v_exp_f32_e32 v163, v163
	v_mfma_f32_16x16x32_bf16 v[130:133], v[204:207], v[2:5], v[130:133]
	v_exp_f32_e32 v164, v164
	v_exp_f32_e32 v165, v165
	v_mfma_f32_16x16x32_bf16 v[126:129], v[208:211], v[2:5], v[126:129]
	v_mfma_f32_16x16x32_bf16 v[122:125], v[212:215], v[2:5], v[122:125]
	s_nop 0
	v_cvt_pk_bf16_f32 v6, v158, v159
	v_cvt_pk_bf16_f32 v7, v160, v161
	v_cvt_pk_bf16_f32 v8, v162, v163
	v_cvt_pk_bf16_f32 v9, v164, v165
	s_waitcnt lgkmcnt(0)
	s_nop 1
	v_mfma_f32_16x16x32_bf16 v[118:121], v[10:13], v[6:9], v[118:121]
	ds_read_b128 v[178:181], v194 offset:16384
	v_mfma_f32_16x16x32_bf16 v[114:117], v[200:203], v[6:9], v[114:117]
	ds_read_b128 v[182:185], v232 offset:16384
	v_mfma_f32_16x16x32_bf16 v[106:109], v[204:207], v[6:9], v[106:109]
	ds_read_b128 v[186:189], v194 offset:18432
	v_mfma_f32_16x16x32_bf16 v[110:113], v[208:211], v[6:9], v[110:113]
	ds_read_b128 v[190:193], v232 offset:18432
	v_mfma_f32_16x16x32_bf16 v[102:105], v[212:215], v[6:9], v[102:105]
	ds_read_b64_tr_b16 v[200:201], v195 offset:18432
	ds_read_b64_tr_b16 v[202:203], v195 offset:20736
	ds_read_b64_tr_b16 v[204:205], v195 offset:18464
	ds_read_b64_tr_b16 v[206:207], v195 offset:20768
	ds_read_b64_tr_b16 v[208:209], v195 offset:18496
	ds_read_b64_tr_b16 v[210:211], v195 offset:20800
	ds_read_b64_tr_b16 v[212:213], v195 offset:18528
	ds_read_b64_tr_b16 v[214:215], v195 offset:20832
	s_branch .Lattn_end2
.Lattn_min2:
	s_waitcnt lgkmcnt(8)
	v_mfma_f32_16x16x32_bf16 v[166:169], v[178:181], v[74:77], v[66:69]
	v_mfma_f32_16x16x32_bf16 v[244:247], v[178:181], v[82:85], v[66:69]
	v_mfma_f32_16x16x32_bf16 v[170:173], v[186:189], v[74:77], v[66:69]
	v_mfma_f32_16x16x32_bf16 v[248:251], v[186:189], v[82:85], v[66:69]
	v_mfma_f32_16x16x32_bf16 v[166:169], v[182:185], v[70:73], v[166:169]
	v_mfma_f32_16x16x32_bf16 v[244:247], v[182:185], v[78:81], v[244:247]
	v_mfma_f32_16x16x32_bf16 v[170:173], v[190:193], v[70:73], v[170:173]
	v_mfma_f32_16x16x32_bf16 v[248:251], v[190:193], v[78:81], v[248:251]
	s_waitcnt lgkmcnt(0)
	ds_read_b128 v[178:181], v194 offset:16384
	ds_read_b128 v[182:185], v232 offset:16384
	ds_read_b128 v[186:189], v194 offset:18432
	ds_read_b128 v[190:193], v232 offset:18432
	ds_read_b64_tr_b16 v[200:201], v195 offset:18432
	ds_read_b64_tr_b16 v[202:203], v195 offset:20736
	ds_read_b64_tr_b16 v[204:205], v195 offset:18464
	ds_read_b64_tr_b16 v[206:207], v195 offset:20768
	ds_read_b64_tr_b16 v[208:209], v195 offset:18496
	ds_read_b64_tr_b16 v[210:211], v195 offset:20800
	ds_read_b64_tr_b16 v[212:213], v195 offset:18528
	ds_read_b64_tr_b16 v[214:215], v195 offset:20832

	.amdhsa_kernel _Z10fwd_kernel6Paramsi
		.amdhsa_group_segment_fixed_size 28688
		.amdhsa_private_segment_fixed_size 0
		.amdhsa_kernarg_size 496
		.amdhsa_user_sgpr_count 2
		.amdhsa_user_sgpr_dispatch_ptr 0
		.amdhsa_user_sgpr_queue_ptr 0
		.amdhsa_user_sgpr_kernarg_segment_ptr 1
		.amdhsa_user_sgpr_dispatch_id 0
		.amdhsa_user_sgpr_kernarg_preload_length 0
		.amdhsa_user_sgpr_kernarg_preload_offset 0
		.amdhsa_user_sgpr_private_segment_size 0
		.amdhsa_uses_dynamic_stack 0
		.amdhsa_enable_private_segment 0
		.amdhsa_system_sgpr_workgroup_id_x 1
		.amdhsa_system_sgpr_workgroup_id_y 0
		.amdhsa_system_sgpr_workgroup_id_z 0
		.amdhsa_system_sgpr_workgroup_info 0
		.amdhsa_system_vgpr_workitem_id 0
		.amdhsa_next_free_vgpr 256
		.amdhsa_next_free_sgpr 102
		.amdhsa_accum_offset 256
		.amdhsa_reserve_vcc 1
		.amdhsa_float_round_mode_32 0
		.amdhsa_float_round_mode_16_64 0
		.amdhsa_float_denorm_mode_32 3
		.amdhsa_float_denorm_mode_16_64 3
		.amdhsa_dx10_clamp 1
		.amdhsa_ieee_mode 1
		.amdhsa_fp16_overflow 0
		.amdhsa_tg_split 0
		.amdhsa_exception_fp_ieee_invalid_op 0
		.amdhsa_exception_fp_denorm_src 0
		.amdhsa_exception_fp_ieee_div_zero 0
		.amdhsa_exception_fp_ieee_overflow 0
		.amdhsa_exception_fp_ieee_underflow 0
		.amdhsa_exception_fp_ieee_inexact 0
		.amdhsa_exception_int_div_zero 0
	.end_amdhsa_kernel

amdhsa.kernels:
  - .agpr_count:     0
    .args:
      - .offset:         0
        .size:           232
        .value_kind:     by_value
      - .offset:         232
        .size:           4
        .value_kind:     by_value
      - .offset:         240
        .size:           4
        .value_kind:     hidden_block_count_x
      - .offset:         244
        .size:           4
        .value_kind:     hidden_block_count_y
      - .offset:         248
        .size:           4
        .value_kind:     hidden_block_count_z
      - .offset:         252
        .size:           2
        .value_kind:     hidden_group_size_x
      - .offset:         254
        .size:           2
        .value_kind:     hidden_group_size_y
      - .offset:         256
        .size:           2
        .value_kind:     hidden_group_size_z
      - .offset:         258
        .size:           2
        .value_kind:     hidden_remainder_x
      - .offset:         260
        .size:           2
        .value_kind:     hidden_remainder_y
      - .offset:         262
        .size:           2
        .value_kind:     hidden_remainder_z
      - .offset:         280
        .size:           8
        .value_kind:     hidden_global_offset_x
      - .offset:         288
        .size:           8
        .value_kind:     hidden_global_offset_y
      - .offset:         296
        .size:           8
        .value_kind:     hidden_global_offset_z
      - .offset:         304
        .size:           2
        .value_kind:     hidden_grid_dims
      - .offset:         360
        .size:           4
        .value_kind:     hidden_dynamic_lds_size
    .group_segment_fixed_size: 28688
    .kernarg_segment_align: 8
    .kernarg_segment_size: 496
    .language:       OpenCL C
    .language_version:
      - 2
      - 0
    .max_flat_workgroup_size: 512
    .name:           _Z10fwd_kernel6Paramsi
    .private_segment_fixed_size: 0
    .sgpr_count:     108
    .sgpr_spill_count: 52
    .symbol:         _Z10fwd_kernel6Paramsi.kd
    .uniform_work_group_size: 1
    .uses_dynamic_stack: false
    .vgpr_count:     256
    .vgpr_spill_count: 0
    .wavefront_size: 64
